# K-loop: LDS reads issued before the loop-carried scalar work; counter and exit test rotated in front of the last load segment's closing wait
# baseline (speedup 1.0000x reference)
; #define PG8_STAGE(bufoff, gbase, voff) do { _Pragma("unroll") for (int _i = 0; _i < 2; ++_i) \
;         __builtin_amdgcn_global_load_lds((const unsigned*)((const char*)(gbase) + (voff)[_i]), (PG8_LAS unsigned*)(lds + (bufoff) + ldsw + _i * 8192), 16, 0, 0); } while (0)
; #define PG8_LDA(dst, b, h) do { _Pragma("unroll") for (int m = 0; m < 4; ++m) _Pragma("unroll") for (int k = 0; k < 2; ++k) dst[m][k] = *(const PG8_LAS bf16x8*)(lds + PG8_SA(b, h) + aoff + m * 2048 + k * 1024); } while (0)
; #define PG8_LDB(dst, b, h) do { _Pragma("unroll") for (int n = 0; n < 2; ++n) _Pragma("unroll") for (int k = 0; k < 2; ++k) dst[n][k] = *(const PG8_LAS bf16x8*)(lds + PG8_SB(b, h) + boff + n * 2048 + k * 1024); } while (0)
; #define PG8_MMA(ai, bj, At, Bt) do { __builtin_amdgcn_s_setprio(1); _Pragma("unroll") for (int m = 0; m < 4; ++m) _Pragma("unroll") for (int n = 0; n < 2; ++n) _Pragma("unroll") for (int k = 0; k < 2; ++k) \
;         acc[ai][bj][m][n] = __builtin_amdgcn_mfma_f32_16x16x32_bf16(Bt[n][k], At[m][k], acc[ai][bj][m][n], 0, 0, 0); __builtin_amdgcn_s_setprio(0); } while (0)
; #define PG8_WAIT_V(n) asm volatile("s_waitcnt vmcnt(" #n ")" ::: "memory")
; #define PG8_WAIT_L(n) asm volatile("s_waitcnt lgkmcnt(" #n ")" ::: "memory")
; #define PG8_BAR __builtin_amdgcn_s_barrier()
; #define PG8_SCHED __builtin_amdgcn_sched_barrier(0)
; template <class Epi, class Sched, bool ALIGN_EPI = false, bool SP2 = false>
; __device__ __forceinline__ void gemm_phase(PG8_LAS unsigned char* lds, const Gemm g, const Sched& S, const Epi& E) {
;     ...
;             const bool last = (t == nt - 2);
;             const char* a1 = cA + (size_t)(t + 1) * kstep;
;             const char* a2 = last ? nA : cA + (size_t)(t + 2) * kstep; const char* b2 = last ? nB : cB + (size_t)(t + 2) * kstep;
;             const char* a3 = a2 + kstep; const char* b3 = b2 + kstep;
;             if (last && has_next) S.a_ready(nxt);
;             if constexpr (SP2) {
;             PG8_LDB(B0, 0, 0); PG8_LDB(B1, 0, 1); PG8_SCHED; PG8_LDA(At, 0, 0); PG8_STAGE(PG8_SA(1, 1), a1 + hstep, voffA);
;             PG8_WAIT_V(8); PG8_WAIT_L(0); PG8_BAR; PG8_MMA(0, 0, At, B0); PG8_MMA(0, 1, At, B1); PG8_BAR; PG8_SCHED;
;             PG8_LDA(At, 0, 1); PG8_STAGE(PG8_SB(0, 0), b2, voffB); PG8_STAGE(PG8_SB(0, 1), b2 + hstep, voffB); PG8_STAGE(PG8_SA(0, 0), a2, voffA);
.LBB0_441:
	s_add_i32 s66, 0, 0x10000
	s_add_i32 s67, 0, 0x14000
	v_add_u32_e32 v142, s66, v228
	v_add_u32_e32 v158, s67, v228
	ds_read_b128 v[130:133], v142
	ds_read_b128 v[134:137], v142 offset:1024
	ds_read_b128 v[138:141], v142 offset:2048
	ds_read_b128 v[142:145], v142 offset:3072
	ds_read_b128 v[146:149], v158
	ds_read_b128 v[150:153], v158 offset:1024
	ds_read_b128 v[154:157], v158 offset:2048
	ds_read_b128 v[158:161], v158 offset:3072
	v_lshl_add_u64 v[206:207], s[42:43], 0, v[190:191]
	s_add_i32 m0, s93, 0xc000
	ds_read_b128 v[162:165], v230
	ds_read_b128 v[166:169], v230 offset:1024
	ds_read_b128 v[170:173], v230 offset:2048
	ds_read_b128 v[174:177], v230 offset:3072
	ds_read_b128 v[178:181], v230 offset:4096
	ds_read_b128 v[194:197], v230 offset:5120
	ds_read_b128 v[198:201], v230 offset:6144
	ds_read_b128 v[202:205], v230 offset:7168
	s_add_i32 s61, s44, 2
	s_add_u32 s64, s42, 0x80
	s_addc_u32 s45, s43, 0
	s_cmp_eq_u32 s99, s44
	s_cselect_b32 s45, s29, s45
	s_cselect_b32 s44, s28, s64
	s_cselect_b32 s65, s21, s60
	s_cselect_b32 s64, s20, s17
	global_load_lds_dwordx4 v[206:207], off
	v_lshl_add_u64 v[206:207], s[42:43], 0, v[192:193]
	s_add_i32 m0, s93, 0xe000
	s_nop 0
	global_load_lds_dwordx4 v[206:207], off
	s_waitcnt vmcnt(8) lgkmcnt(0)
	s_barrier
	s_setprio 1
	v_mfma_f32_16x16x32_bf16 v[126:129], v[130:133], v[162:165], v[126:129]
	v_mfma_f32_16x16x32_bf16 v[122:125], v[138:141], v[162:165], v[122:125]
	v_mfma_f32_16x16x32_bf16 v[110:113], v[130:133], v[170:173], v[110:113]
	v_mfma_f32_16x16x32_bf16 v[102:105], v[138:141], v[170:173], v[102:105]
	v_mfma_f32_16x16x32_bf16 v[94:97], v[130:133], v[178:181], v[94:97]
	v_mfma_f32_16x16x32_bf16 v[86:89], v[138:141], v[178:181], v[86:89]
	v_mfma_f32_16x16x32_bf16 v[78:81], v[130:133], v[198:201], v[78:81]
	v_mfma_f32_16x16x32_bf16 v[70:73], v[138:141], v[198:201], v[70:73]
	v_mfma_f32_16x16x32_bf16 v[126:129], v[134:137], v[166:169], v[126:129]
	v_mfma_f32_16x16x32_bf16 v[122:125], v[142:145], v[166:169], v[122:125]
	v_mfma_f32_16x16x32_bf16 v[110:113], v[134:137], v[174:177], v[110:113]
	v_mfma_f32_16x16x32_bf16 v[102:105], v[142:145], v[174:177], v[102:105]
	v_mfma_f32_16x16x32_bf16 v[94:97], v[134:137], v[194:197], v[94:97]
	v_mfma_f32_16x16x32_bf16 v[86:89], v[142:145], v[194:197], v[86:89]
	v_mfma_f32_16x16x32_bf16 v[78:81], v[134:137], v[202:205], v[78:81]
	v_mfma_f32_16x16x32_bf16 v[70:73], v[142:145], v[202:205], v[70:73]
	v_mfma_f32_16x16x32_bf16 v[118:121], v[146:149], v[162:165], v[118:121]
	v_mfma_f32_16x16x32_bf16 v[114:117], v[154:157], v[162:165], v[114:117]
	v_mfma_f32_16x16x32_bf16 v[106:109], v[146:149], v[170:173], v[106:109]
	v_mfma_f32_16x16x32_bf16 v[98:101], v[154:157], v[170:173], v[98:101]
	v_mfma_f32_16x16x32_bf16 v[90:93], v[146:149], v[178:181], v[90:93]
	v_mfma_f32_16x16x32_bf16 v[82:85], v[154:157], v[178:181], v[82:85]
	v_mfma_f32_16x16x32_bf16 v[74:77], v[146:149], v[198:201], v[74:77]
	v_mfma_f32_16x16x32_bf16 v[66:69], v[154:157], v[198:201], v[66:69]
	v_mfma_f32_16x16x32_bf16 v[118:121], v[150:153], v[166:169], v[118:121]
	v_mfma_f32_16x16x32_bf16 v[114:117], v[158:161], v[166:169], v[114:117]
	v_mfma_f32_16x16x32_bf16 v[106:109], v[150:153], v[174:177], v[106:109]
	v_mfma_f32_16x16x32_bf16 v[98:101], v[158:161], v[174:177], v[98:101]
	v_mfma_f32_16x16x32_bf16 v[90:93], v[150:153], v[194:197], v[90:93]
	v_mfma_f32_16x16x32_bf16 v[82:85], v[158:161], v[194:197], v[82:85]
	v_mfma_f32_16x16x32_bf16 v[74:77], v[150:153], v[202:205], v[74:77]
	v_mfma_f32_16x16x32_bf16 v[66:69], v[158:161], v[202:205], v[66:69]
	s_setprio 0
	s_barrier
	s_add_i32 s66, s66, s92
	v_lshl_add_u64 v[206:207], s[64:65], 0, v[184:185]
	s_mov_b32 m0, s66
	ds_read_b128 v[162:165], v230 offset:16384
	ds_read_b128 v[166:169], v230 offset:17408
	ds_read_b128 v[170:173], v230 offset:18432
	ds_read_b128 v[174:177], v230 offset:19456
	ds_read_b128 v[178:181], v230 offset:20480
	ds_read_b128 v[194:197], v230 offset:21504
	ds_read_b128 v[198:201], v230 offset:22528
	ds_read_b128 v[202:205], v230 offset:23552
	global_load_lds_dwordx4 v[206:207], off
	s_add_i32 m0, s66, 0x2000
	v_lshl_add_u64 v[208:209], s[64:65], 0, v[188:189]
	s_add_u32 s64, s64, s26
	s_addc_u32 s65, s65, 0
	s_add_i32 s66, s67, s92
	global_load_lds_dwordx4 v[208:209], off
	v_lshl_add_u64 v[210:211], s[64:65], 0, v[184:185]
	s_mov_b32 m0, s66
	v_lshl_add_u64 v[232:233], s[64:65], 0, v[188:189]
	global_load_lds_dwordx4 v[210:211], off
	s_add_i32 m0, s66, 0x2000
	v_lshl_add_u64 v[234:235], s[44:45], 0, v[182:183]
	global_load_lds_dwordx4 v[232:233], off
	s_mov_b32 m0, s93
	v_lshl_add_u64 v[236:237], s[44:45], 0, v[186:187]
	global_load_lds_dwordx4 v[234:235], off
	s_mov_b32 m0, s94
	s_nop 0
	global_load_lds_dwordx4 v[236:237], off
	s_waitcnt vmcnt(8) lgkmcnt(0)
	s_barrier
; #define PG8_STAGE(bufoff, gbase, voff) do { _Pragma("unroll") for (int _i = 0; _i < 2; ++_i) \
;         __builtin_amdgcn_global_load_lds((const unsigned*)((const char*)(gbase) + (voff)[_i]), (PG8_LAS unsigned*)(lds + (bufoff) + ldsw + _i * 8192), 16, 0, 0); } while (0)
; #define PG8_LDA(dst, b, h) do { _Pragma("unroll") for (int m = 0; m < 4; ++m) _Pragma("unroll") for (int k = 0; k < 2; ++k) dst[m][k] = *(const PG8_LAS bf16x8*)(lds + PG8_SA(b, h) + aoff + m * 2048 + k * 1024); } while (0)
; #define PG8_LDB(dst, b, h) do { _Pragma("unroll") for (int n = 0; n < 2; ++n) _Pragma("unroll") for (int k = 0; k < 2; ++k) dst[n][k] = *(const PG8_LAS bf16x8*)(lds + PG8_SB(b, h) + boff + n * 2048 + k * 1024); } while (0)
; #define PG8_MMA(ai, bj, At, Bt) do { __builtin_amdgcn_s_setprio(1); _Pragma("unroll") for (int m = 0; m < 4; ++m) _Pragma("unroll") for (int n = 0; n < 2; ++n) _Pragma("unroll") for (int k = 0; k < 2; ++k) \
;         acc[ai][bj][m][n] = __builtin_amdgcn_mfma_f32_16x16x32_bf16(Bt[n][k], At[m][k], acc[ai][bj][m][n], 0, 0, 0); __builtin_amdgcn_s_setprio(0); } while (0)
; #define PG8_WAIT_V(n) asm volatile("s_waitcnt vmcnt(" #n ")" ::: "memory")
; #define PG8_WAIT_L(n) asm volatile("s_waitcnt lgkmcnt(" #n ")" ::: "memory")
; #define PG8_BAR __builtin_amdgcn_s_barrier()
; #define PG8_SCHED __builtin_amdgcn_sched_barrier(0)
; template <class Epi, class Sched, bool ALIGN_EPI = false, bool SP2 = false>
; __device__ __forceinline__ void gemm_phase(PG8_LAS unsigned char* lds, const Gemm g, const Sched& S, const Epi& E) {
;     ...
;             PG8_WAIT_V(8); PG8_WAIT_L(0); PG8_BAR; PG8_MMA(1, 0, At, B0); PG8_MMA(1, 1, At, B1); PG8_BAR; PG8_SCHED;
;             PG8_LDB(B0, 1, 0); PG8_LDB(B1, 1, 1); PG8_SCHED; PG8_LDA(At, 1, 0); PG8_STAGE(PG8_SA(0, 1), a2 + hstep, voffA);
;             PG8_WAIT_V(8); PG8_WAIT_L(0); PG8_BAR; PG8_MMA(0, 0, At, B0); PG8_MMA(0, 1, At, B1); PG8_BAR; PG8_SCHED;
	s_setprio 1
	v_mfma_f32_16x16x32_bf16 v[62:65], v[130:133], v[162:165], v[62:65]
	v_mfma_f32_16x16x32_bf16 v[54:57], v[138:141], v[162:165], v[54:57]
	v_mfma_f32_16x16x32_bf16 v[46:49], v[130:133], v[170:173], v[46:49]
	v_mfma_f32_16x16x32_bf16 v[38:41], v[138:141], v[170:173], v[38:41]
	v_mfma_f32_16x16x32_bf16 v[30:33], v[130:133], v[178:181], v[30:33]
	v_mfma_f32_16x16x32_bf16 v[22:25], v[138:141], v[178:181], v[22:25]
	v_mfma_f32_16x16x32_bf16 v[14:17], v[130:133], v[198:201], v[14:17]
	v_mfma_f32_16x16x32_bf16 v[6:9], v[138:141], v[198:201], v[6:9]
	v_mfma_f32_16x16x32_bf16 v[62:65], v[134:137], v[166:169], v[62:65]
	v_mfma_f32_16x16x32_bf16 v[54:57], v[142:145], v[166:169], v[54:57]
	v_mfma_f32_16x16x32_bf16 v[46:49], v[134:137], v[174:177], v[46:49]
	v_mfma_f32_16x16x32_bf16 v[38:41], v[142:145], v[174:177], v[38:41]
	v_mfma_f32_16x16x32_bf16 v[30:33], v[134:137], v[194:197], v[30:33]
	v_mfma_f32_16x16x32_bf16 v[22:25], v[142:145], v[194:197], v[22:25]
	v_mfma_f32_16x16x32_bf16 v[14:17], v[134:137], v[202:205], v[14:17]
	v_mfma_f32_16x16x32_bf16 v[6:9], v[142:145], v[202:205], v[6:9]
	v_mfma_f32_16x16x32_bf16 v[58:61], v[146:149], v[162:165], v[58:61]
	v_mfma_f32_16x16x32_bf16 v[50:53], v[154:157], v[162:165], v[50:53]
	v_mfma_f32_16x16x32_bf16 v[42:45], v[146:149], v[170:173], v[42:45]
	v_mfma_f32_16x16x32_bf16 v[34:37], v[154:157], v[170:173], v[34:37]
	v_mfma_f32_16x16x32_bf16 v[26:29], v[146:149], v[178:181], v[26:29]
	v_mfma_f32_16x16x32_bf16 v[18:21], v[154:157], v[178:181], v[18:21]
	v_mfma_f32_16x16x32_bf16 v[10:13], v[146:149], v[198:201], v[10:13]
	v_mfma_f32_16x16x32_bf16 v[2:5], v[154:157], v[198:201], v[2:5]
	v_mfma_f32_16x16x32_bf16 v[58:61], v[150:153], v[166:169], v[58:61]
	v_mfma_f32_16x16x32_bf16 v[50:53], v[158:161], v[166:169], v[50:53]
	v_mfma_f32_16x16x32_bf16 v[42:45], v[150:153], v[174:177], v[42:45]
	v_mfma_f32_16x16x32_bf16 v[34:37], v[158:161], v[174:177], v[34:37]
	v_mfma_f32_16x16x32_bf16 v[26:29], v[150:153], v[194:197], v[26:29]
	v_mfma_f32_16x16x32_bf16 v[18:21], v[158:161], v[194:197], v[18:21]
	v_mfma_f32_16x16x32_bf16 v[10:13], v[150:153], v[202:205], v[10:13]
	v_mfma_f32_16x16x32_bf16 v[2:5], v[158:161], v[202:205], v[2:5]
	s_setprio 0
	s_barrier
	s_add_i32 s64, 0, 0x18000
	s_add_i32 s65, 0, 0x1c000
	v_add_u32_e32 v142, s64, v228
	v_add_u32_e32 v158, s65, v228
	ds_read_b128 v[130:133], v142
	ds_read_b128 v[134:137], v142 offset:1024
	ds_read_b128 v[138:141], v142 offset:2048
	ds_read_b128 v[142:145], v142 offset:3072
	ds_read_b128 v[146:149], v158
	ds_read_b128 v[150:153], v158 offset:1024
	ds_read_b128 v[154:157], v158 offset:2048
	ds_read_b128 v[158:161], v158 offset:3072
	s_add_u32 s44, s44, s26
	s_addc_u32 s45, s45, 0
	s_mov_b32 m0, s95
	v_lshl_add_u64 v[238:239], s[44:45], 0, v[182:183]
	ds_read_b128 v[162:165], v230 offset:32768
	ds_read_b128 v[166:169], v230 offset:33792
	ds_read_b128 v[170:173], v230 offset:34816
	ds_read_b128 v[174:177], v230 offset:35840
	ds_read_b128 v[178:181], v230 offset:36864
	ds_read_b128 v[194:197], v230 offset:37888
	ds_read_b128 v[198:201], v230 offset:38912
	ds_read_b128 v[202:205], v230 offset:39936
	global_load_lds_dwordx4 v[238:239], off
	v_lshl_add_u64 v[238:239], s[44:45], 0, v[186:187]
	s_mov_b32 m0, s96
	s_nop 0
	global_load_lds_dwordx4 v[238:239], off
	s_waitcnt vmcnt(8) lgkmcnt(0)
	s_barrier
	s_setprio 1
	v_mfma_f32_16x16x32_bf16 v[126:129], v[130:133], v[162:165], v[126:129]
	v_mfma_f32_16x16x32_bf16 v[122:125], v[138:141], v[162:165], v[122:125]
	v_mfma_f32_16x16x32_bf16 v[110:113], v[130:133], v[170:173], v[110:113]
	v_mfma_f32_16x16x32_bf16 v[102:105], v[138:141], v[170:173], v[102:105]
	v_mfma_f32_16x16x32_bf16 v[94:97], v[130:133], v[178:181], v[94:97]
	v_mfma_f32_16x16x32_bf16 v[86:89], v[138:141], v[178:181], v[86:89]
	v_mfma_f32_16x16x32_bf16 v[78:81], v[130:133], v[198:201], v[78:81]
	v_mfma_f32_16x16x32_bf16 v[70:73], v[138:141], v[198:201], v[70:73]
	v_mfma_f32_16x16x32_bf16 v[126:129], v[134:137], v[166:169], v[126:129]
	v_mfma_f32_16x16x32_bf16 v[122:125], v[142:145], v[166:169], v[122:125]
	v_mfma_f32_16x16x32_bf16 v[110:113], v[134:137], v[174:177], v[110:113]
	v_mfma_f32_16x16x32_bf16 v[102:105], v[142:145], v[174:177], v[102:105]
	v_mfma_f32_16x16x32_bf16 v[94:97], v[134:137], v[194:197], v[94:97]
	v_mfma_f32_16x16x32_bf16 v[86:89], v[142:145], v[194:197], v[86:89]
	v_mfma_f32_16x16x32_bf16 v[78:81], v[134:137], v[202:205], v[78:81]
	v_mfma_f32_16x16x32_bf16 v[70:73], v[142:145], v[202:205], v[70:73]
	v_mfma_f32_16x16x32_bf16 v[118:121], v[146:149], v[162:165], v[118:121]
	v_mfma_f32_16x16x32_bf16 v[114:117], v[154:157], v[162:165], v[114:117]
	v_mfma_f32_16x16x32_bf16 v[106:109], v[146:149], v[170:173], v[106:109]
	v_mfma_f32_16x16x32_bf16 v[98:101], v[154:157], v[170:173], v[98:101]
	v_mfma_f32_16x16x32_bf16 v[90:93], v[146:149], v[178:181], v[90:93]
	v_mfma_f32_16x16x32_bf16 v[82:85], v[154:157], v[178:181], v[82:85]
	v_mfma_f32_16x16x32_bf16 v[74:77], v[146:149], v[198:201], v[74:77]
	v_mfma_f32_16x16x32_bf16 v[66:69], v[154:157], v[198:201], v[66:69]
	v_mfma_f32_16x16x32_bf16 v[118:121], v[150:153], v[166:169], v[118:121]
	v_mfma_f32_16x16x32_bf16 v[114:117], v[158:161], v[166:169], v[114:117]
	v_mfma_f32_16x16x32_bf16 v[106:109], v[150:153], v[174:177], v[106:109]
	v_mfma_f32_16x16x32_bf16 v[98:101], v[158:161], v[174:177], v[98:101]
	v_mfma_f32_16x16x32_bf16 v[90:93], v[150:153], v[194:197], v[90:93]
	v_mfma_f32_16x16x32_bf16 v[82:85], v[158:161], v[194:197], v[82:85]
	v_mfma_f32_16x16x32_bf16 v[74:77], v[150:153], v[202:205], v[74:77]
	v_mfma_f32_16x16x32_bf16 v[66:69], v[158:161], v[202:205], v[66:69]
	s_setprio 0
	s_barrier
; #define PG8_STAGE(bufoff, gbase, voff) do { _Pragma("unroll") for (int _i = 0; _i < 2; ++_i) \
;         __builtin_amdgcn_global_load_lds((const unsigned*)((const char*)(gbase) + (voff)[_i]), (PG8_LAS unsigned*)(lds + (bufoff) + ldsw + _i * 8192), 16, 0, 0); } while (0)
; #define PG8_LDA(dst, b, h) do { _Pragma("unroll") for (int m = 0; m < 4; ++m) _Pragma("unroll") for (int k = 0; k < 2; ++k) dst[m][k] = *(const PG8_LAS bf16x8*)(lds + PG8_SA(b, h) + aoff + m * 2048 + k * 1024); } while (0)
; #define PG8_MMA(ai, bj, At, Bt) do { __builtin_amdgcn_s_setprio(1); _Pragma("unroll") for (int m = 0; m < 4; ++m) _Pragma("unroll") for (int n = 0; n < 2; ++n) _Pragma("unroll") for (int k = 0; k < 2; ++k) \
;         acc[ai][bj][m][n] = __builtin_amdgcn_mfma_f32_16x16x32_bf16(Bt[n][k], At[m][k], acc[ai][bj][m][n], 0, 0, 0); __builtin_amdgcn_s_setprio(0); } while (0)
; #define PG8_WAIT_V(n) asm volatile("s_waitcnt vmcnt(" #n ")" ::: "memory")
; #define PG8_WAIT_L(n) asm volatile("s_waitcnt lgkmcnt(" #n ")" ::: "memory")
; #define PG8_BAR __builtin_amdgcn_s_barrier()
; #define PG8_SCHED __builtin_amdgcn_sched_barrier(0)
; template <class Epi, class Sched, bool ALIGN_EPI = false, bool SP2 = false>
; __device__ __forceinline__ void gemm_phase(PG8_LAS unsigned char* lds, const Gemm g, const Sched& S, const Epi& E) {
;     ...
;             PG8_LDA(At, 1, 1); PG8_STAGE(PG8_SB(1, 0), b3, voffB); PG8_STAGE(PG8_SB(1, 1), b3 + hstep, voffB); PG8_STAGE(PG8_SA(1, 0), a3, voffA);
;             PG8_WAIT_V(8); PG8_WAIT_L(0); PG8_BAR; PG8_MMA(1, 0, At, B0); PG8_MMA(1, 1, At, B1); PG8_BAR; PG8_SCHED;
;     ...
;         if constexpr (ALIGN_EPI) { if (wr == 0) PG8_BAR; }
;         if constexpr (!Epi::AFTER_DRAIN) { E(acc, cur, wr, wc, fr, fq); S.done(cur); }
	s_add_i32 s44, s64, s92
	v_lshl_add_u64 v[206:207], v[206:207], 0, s[34:35]
	s_mov_b32 m0, s44
	ds_read_b128 v[162:165], v230 offset:49152
	ds_read_b128 v[166:169], v230 offset:50176
	ds_read_b128 v[170:173], v230 offset:51200
	ds_read_b128 v[174:177], v230 offset:52224
	ds_read_b128 v[178:181], v230 offset:53248
	ds_read_b128 v[194:197], v230 offset:54272
	ds_read_b128 v[198:201], v230 offset:55296
	ds_read_b128 v[202:205], v230 offset:56320
	global_load_lds_dwordx4 v[206:207], off
	v_lshl_add_u64 v[206:207], v[208:209], 0, s[34:35]
	s_add_i32 m0, s44, 0x2000
	s_add_i32 s44, s65, s92
	global_load_lds_dwordx4 v[206:207], off
	v_lshl_add_u64 v[206:207], v[210:211], 0, s[34:35]
	s_mov_b32 m0, s44
	s_nop 0
	global_load_lds_dwordx4 v[206:207], off
	v_lshl_add_u64 v[206:207], v[232:233], 0, s[34:35]
	s_add_i32 m0, s44, 0x2000
	s_nop 0
	global_load_lds_dwordx4 v[206:207], off
	v_lshl_add_u64 v[206:207], v[234:235], 0, s[34:35]
	s_mov_b32 m0, s97
	s_nop 0
	global_load_lds_dwordx4 v[206:207], off
	v_lshl_add_u64 v[206:207], v[236:237], 0, s[34:35]
	s_mov_b32 m0, s98
	s_nop 0
	global_load_lds_dwordx4 v[206:207], off
	s_add_u32 s42, s42, 0x100
	s_addc_u32 s43, s43, 0
	s_add_u32 s17, s17, 0x100
	s_addc_u32 s60, s60, 0
	s_cmp_ge_u32 s61, s4
	s_mov_b32 s44, s61
	s_waitcnt vmcnt(8) lgkmcnt(0)
	s_barrier
	s_setprio 1
	v_mfma_f32_16x16x32_bf16 v[62:65], v[130:133], v[162:165], v[62:65]
	v_mfma_f32_16x16x32_bf16 v[54:57], v[138:141], v[162:165], v[54:57]
	v_mfma_f32_16x16x32_bf16 v[46:49], v[130:133], v[170:173], v[46:49]
	v_mfma_f32_16x16x32_bf16 v[38:41], v[138:141], v[170:173], v[38:41]
	v_mfma_f32_16x16x32_bf16 v[30:33], v[130:133], v[178:181], v[30:33]
	v_mfma_f32_16x16x32_bf16 v[22:25], v[138:141], v[178:181], v[22:25]
	v_mfma_f32_16x16x32_bf16 v[14:17], v[130:133], v[198:201], v[14:17]
	v_mfma_f32_16x16x32_bf16 v[6:9], v[138:141], v[198:201], v[6:9]
	v_mfma_f32_16x16x32_bf16 v[62:65], v[134:137], v[166:169], v[62:65]
	v_mfma_f32_16x16x32_bf16 v[54:57], v[142:145], v[166:169], v[54:57]
	v_mfma_f32_16x16x32_bf16 v[46:49], v[134:137], v[174:177], v[46:49]
	v_mfma_f32_16x16x32_bf16 v[38:41], v[142:145], v[174:177], v[38:41]
	v_mfma_f32_16x16x32_bf16 v[30:33], v[134:137], v[194:197], v[30:33]
	v_mfma_f32_16x16x32_bf16 v[22:25], v[142:145], v[194:197], v[22:25]
	v_mfma_f32_16x16x32_bf16 v[14:17], v[134:137], v[202:205], v[14:17]
	v_mfma_f32_16x16x32_bf16 v[6:9], v[142:145], v[202:205], v[6:9]
	v_mfma_f32_16x16x32_bf16 v[58:61], v[146:149], v[162:165], v[58:61]
	v_mfma_f32_16x16x32_bf16 v[50:53], v[154:157], v[162:165], v[50:53]
	v_mfma_f32_16x16x32_bf16 v[42:45], v[146:149], v[170:173], v[42:45]
	v_mfma_f32_16x16x32_bf16 v[34:37], v[154:157], v[170:173], v[34:37]
	v_mfma_f32_16x16x32_bf16 v[26:29], v[146:149], v[178:181], v[26:29]
	v_mfma_f32_16x16x32_bf16 v[18:21], v[154:157], v[178:181], v[18:21]
	v_mfma_f32_16x16x32_bf16 v[10:13], v[146:149], v[198:201], v[10:13]
	v_mfma_f32_16x16x32_bf16 v[2:5], v[154:157], v[198:201], v[2:5]
	v_mfma_f32_16x16x32_bf16 v[58:61], v[150:153], v[166:169], v[58:61]
	v_mfma_f32_16x16x32_bf16 v[50:53], v[158:161], v[166:169], v[50:53]
	v_mfma_f32_16x16x32_bf16 v[42:45], v[150:153], v[174:177], v[42:45]
	v_mfma_f32_16x16x32_bf16 v[34:37], v[158:161], v[174:177], v[34:37]
	v_mfma_f32_16x16x32_bf16 v[26:29], v[150:153], v[194:197], v[26:29]
	v_mfma_f32_16x16x32_bf16 v[18:21], v[158:161], v[194:197], v[18:21]
	v_mfma_f32_16x16x32_bf16 v[10:13], v[150:153], v[202:205], v[10:13]
	v_mfma_f32_16x16x32_bf16 v[2:5], v[158:161], v[202:205], v[2:5]
	s_setprio 0
	s_barrier
	s_cbranch_scc0 .LBB0_441
	s_and_b64 vcc, exec, s[36:37]
	s_cbranch_vccz .LBB0_445
	s_barrier
	s_cmp_lt_i32 s0, 2
	s_mov_b64 s[42:43], -1
	s_cbranch_scc0 .LBB0_446
